# P7: workgroups owning a split-K sample tile run it first (offsets their epilogue bursts from the other 192), guarded by gridDim==256
# speedup vs baseline: 1.0193x; 1.0023x over previous
.LBB0_1491:
	s_or_b64 exec, exec, s[0:1]
	s_add_u32 s6, s50, 0x24d4d700
	s_addc_u32 s7, s51, 0
	s_add_u32 s4, s48, 0x9b5c000
	s_addc_u32 s5, s49, 0
	v_readlane_b32 s0, v254, 50
	s_cmpk_gt_i32 s0, 0x23f
	s_waitcnt lgkmcnt(0)
	s_barrier
	v_readlane_b32 s1, v254, 51
	s_cbranch_scc1 .LBB0_1590
	s_add_u32 s2, s50, 0x26c0000
	s_addc_u32 s11, s51, 0
	s_add_u32 s8, s48, 0x9600000
	v_readlane_b32 s0, v254, 50
	s_addc_u32 s9, s49, 0
	s_lshl_b32 s19, s0, 10
	s_lshl_b32 s25, s92, 10
	s_add_i32 s10, s0, 0xfffffe00
	s_lshl_b32 s33, s0, 18
	s_lshl_b32 s56, s92, 18
	s_mov_b32 s13, 0
	s_mov_b64 s[20:21], 0x80
	s_mov_b64 s[22:23], 0x69dd780
	s_mov_b64 s[26:27], 0x26c0100
	s_mov_b64 s[28:29], 0x695d800
	s_mov_b64 s[30:31], 0x2740100
	s_mov_b64 s[40:41], 0x69dd800
	s_mov_b64 s[44:45], 0x26c0180
	s_mov_b64 s[54:55], 0x695d880
	s_mov_b64 s[58:59], 0x2740180
	s_mov_b64 s[60:61], 0x100
	v_mov_b32_e32 v129, 0
	s_mov_b64 s[62:63], 0x49dd780
	s_mov_b64 s[64:65], 0x495d800
	s_mov_b64 s[66:67], 0x49dd800
	s_mov_b64 s[68:69], 0x495d880
	s_mov_b64 s[70:71], 0xc05c700
	s_movk_i32 s57, 0x1fff
	s_movk_i32 s86, 0xff0
	v_mov_b32_e32 v148, 1
	s_mov_b32 s87, s0
	v_readlane_b32 s1, v254, 51
	s_mov_b32 s98, 0
	s_mov_b32 s100, s0
	s_cmpk_eq_u32 s92, 0x100
	s_cbranch_scc0 .Lp7_pre_done
	s_mov_b32 s98, 1
	s_cmpk_lt_u32 s0, 0x40
	s_cbranch_scc0 .Lp7_pre_done
	s_add_i32 s87, s0, 0x200
	s_mov_b32 s100, s87
.Lp7_pre_done:
	s_branch .LBB0_1495
.LBB0_1493:
	s_or_b64 exec, exec, s[0:1]
.LBB0_1494:
	s_and_b64 vcc, exec, s[72:73]
	s_cbranch_vccnz .LBB0_1590
.LBB0_1495:
	s_mov_b32 s88, s87
	s_add_i32 s87, s87, s92
	s_cmpk_gt_i32 s87, 0x23f
	s_cselect_b64 s[72:73], -1, 0
	s_cmp_eq_u32 s98, 0
	s_cbranch_scc1 .Lp7_hd_done
	s_movk_i32 s99, 0x100
	s_cmpk_ge_u32 s88, 0x200
	s_cselect_b32 s99, 0xfffffe00, s99
	s_add_i32 s87, s88, s99
	s_cmpk_lt_u32 s87, 0x200
	s_cselect_b64 s[72:73], 0, -1
.Lp7_hd_done:
	s_lshl_b32 s19, s88, 10
	s_add_i32 s10, s88, 0xfffffe00
	s_lshl_b32 s33, s88, 18
	s_and_b64 vcc, exec, s[72:73]
	s_mov_b64 s[74:75], 0
	s_mov_b64 s[0:1], 0
	s_cbranch_vccnz .LBB0_1504
	s_cmpk_gt_i32 s87, 0x1ff
	s_mov_b64 s[76:77], -1
	s_cbranch_scc0 .LBB0_1498
	s_add_i32 s0, s87, 0xfffffe00
	s_lshr_b32 s12, s0, 2
	s_lshl_b32 s0, s87, 19
	s_and_b32 s0, s0, 0x100000
	s_add_u32 s0, s50, s0
	s_addc_u32 s1, s51, 0
	s_lshl_b32 s74, s87, 11
	s_and_b32 s76, s74, 0x800
	s_add_u32 s0, s0, s76
	s_addc_u32 s1, s1, 0
	s_add_u32 s0, s0, 0x695d700
	s_addc_u32 s1, s1, 0
	s_lshl_b64 s[74:75], s[12:13], 20
	s_add_u32 s12, s2, s74
	s_addc_u32 s75, s11, s75
	s_add_u32 s74, s12, s76
	s_addc_u32 s75, s75, 0
	s_mov_b64 s[76:77], 0

.LBB0_1504:
	s_cmpk_gt_i32 s88, 0x1ff
	s_mov_b64 s[76:77], -1
	s_cbranch_scc0 .LBB0_1516
	v_mov_b32_e32 v8, v250
	s_add_i32 s12, s88, 0xfffffe00
	v_bfe_i32 v1, v8, 27, 1
	v_lshlrev_b32_e32 v2, 4, v8
	v_lshrrev_b32_e32 v1, 22, v1
	v_add_u32_e32 v1, v2, v1
	v_and_b32_e32 v1, 0xfffffc00, v1
	v_ashrrev_i32_e32 v0, 31, v8
	v_sub_u32_e32 v1, v2, v1
	v_lshrrev_b32_e32 v0, 26, v0
	v_lshrrev_b32_e32 v3, 4, v1
	v_add_u32_e32 v0, v8, v0
	v_bitop3_b32 v4, v3, v1, 32 bitop3:0x6c
	v_ashrrev_i32_e32 v1, 31, v1
	v_ashrrev_i32_e32 v0, 6, v0
	v_lshrrev_b32_e32 v1, 26, v1
	v_lshlrev_b32_e32 v3, 3, v0
	v_add_u32_e32 v1, v4, v1
	v_and_b32_e32 v3, 0x1ffff0, v3
	v_ashrrev_i32_e32 v1, 6, v1
	v_add_u32_e32 v5, v1, v3
	v_lshlrev_b32_e32 v3, 5, v0
	v_mul_i32_i24_e32 v6, 64, v1
	v_and_b32_e32 v3, 32, v3
	v_sub_u32_e32 v4, v4, v6
	v_ashrrev_i16_sdwa v4, v148, sext(v4) dst_sel:DWORD dst_unused:UNUSED_PAD src0_sel:DWORD src1_sel:BYTE_0
	v_lshl_or_b32 v5, v5, 11, v3
	v_add_u32_sdwa v136, v5, sext(v4) dst_sel:DWORD dst_unused:UNUSED_PAD src0_sel:DWORD src1_sel:WORD_0
	v_add_u32_e32 v5, 0x2000, v2
	s_lshr_b32 s76, s12, 2
	s_lshl_b32 s12, s88, 19
	v_ashrrev_i32_e32 v2, 31, v5
	s_and_b32 s12, s12, 0x100000
	v_lshrrev_b32_e32 v2, 22, v2
	s_add_u32 s12, s50, s12
	v_add_u32_e32 v2, v5, v2
	s_addc_u32 s77, s51, 0
	s_lshl_b32 s78, s88, 11
	v_ashrrev_i32_e32 v2, 10, v2
	s_and_b32 s82, s78, 0x800
	v_mul_i32_i24_e32 v6, 0x400, v2
	s_add_u32 s12, s12, s82
	v_sub_u32_e32 v5, v5, v6
	s_addc_u32 s77, s77, 0
	v_lshrrev_b32_e32 v6, 4, v5
	s_add_u32 s78, s12, 0x695d700
	v_bitop3_b32 v7, v6, v5, 32 bitop3:0x6c
	v_lshlrev_b32_e32 v5, 3, v2
	s_addc_u32 s79, s77, 0
	s_mov_b32 s77, s13
	v_and_b32_e32 v6, 0x1ffff0, v5
	v_ashrrev_i32_e32 v5, 31, v7
	s_lshl_b64 s[80:81], s[76:77], 20
	v_lshrrev_b32_e32 v5, 26, v5
	s_add_u32 s12, s2, s80
	v_add_u32_e32 v9, v7, v5
	s_addc_u32 s77, s11, s81
	v_ashrrev_i32_e32 v5, 6, v9
	s_add_u32 s80, s12, s82
	v_add_u32_e32 v10, v5, v6
	v_lshlrev_b32_e32 v6, 5, v2
	v_and_b32_e32 v9, 0xc0, v9
	s_addc_u32 s81, s77, 0
	v_readfirstlane_b32 s77, v8
	v_and_b32_e32 v6, 32, v6
	v_sub_u32_e32 v7, v7, v9
	s_ashr_i32 s12, s77, 6
	v_ashrrev_i16_sdwa v7, v148, sext(v7) dst_sel:DWORD dst_unused:UNUSED_PAD src0_sel:DWORD src1_sel:BYTE_0
	v_lshl_or_b32 v9, v10, 11, v6
	s_lshl_b32 s84, s12, 10
	v_readlane_b32 s82, v254, 50
	v_add_u32_sdwa v138, v9, sext(v7) dst_sel:DWORD dst_unused:UNUSED_PAD src0_sel:DWORD src1_sel:WORD_0
	s_cmp_lg_u32 s88, s100
	v_ashrrev_i32_e32 v137, 31, v136
	v_ashrrev_i32_e32 v139, 31, v138
	v_readlane_b32 s83, v254, 51
	s_cbranch_scc1 .LBB0_1507
	s_add_i32 s85, s84, 32
	v_lshlrev_b64 v[10:11], 1, v[136:137]
	s_add_i32 m0, s85, 0x10000
	v_lshl_add_u64 v[12:13], s[80:81], 0, v[10:11]
	global_load_lds_dwordx4 v[12:13], off
	v_lshlrev_b64 v[12:13], 1, v[138:139]
	v_lshl_add_u64 v[14:15], s[80:81], 0, v[12:13]
	s_add_i32 m0, s85, 0x12000
	s_nop 0
	global_load_lds_dwordx4 v[14:15], off
	v_lshl_add_u64 v[14:15], s[78:79], 0, v[10:11]
	s_mov_b32 m0, s85
	s_nop 0
	global_load_lds_dwordx4 v[14:15], off
	s_add_i32 m0, s85, 0x2000
	s_add_u32 s82, s80, 0x80000
	v_lshl_add_u64 v[14:15], s[78:79], 0, v[12:13]
	s_addc_u32 s83, s81, 0
	global_load_lds_dwordx4 v[14:15], off
	s_add_i32 m0, s85, 0x14000
	v_lshl_add_u64 v[14:15], s[82:83], 0, v[10:11]
	global_load_lds_dwordx4 v[14:15], off
	s_add_i32 m0, s85, 0x16000
	v_lshl_add_u64 v[14:15], s[82:83], 0, v[12:13]
	s_add_u32 s82, s78, 0x80000
	s_addc_u32 s83, s79, 0
	global_load_lds_dwordx4 v[14:15], off
	s_add_i32 m0, s85, 0x4000
	v_lshl_add_u64 v[10:11], s[82:83], 0, v[10:11]
	global_load_lds_dwordx4 v[10:11], off
	v_lshl_add_u64 v[10:11], s[82:83], 0, v[12:13]
	s_add_i32 m0, s85, 0x6000
	s_nop 0
	global_load_lds_dwordx4 v[10:11], off

.LBB0_1521:
	v_mov_b32_e32 v8, v250
	s_ashr_i32 s12, s12, 3
	v_bfe_i32 v1, v8, 27, 1
	v_lshlrev_b32_e32 v4, 4, v8
	v_lshrrev_b32_e32 v1, 22, v1
	v_add_u32_e32 v1, v4, v1
	v_and_b32_e32 v1, 0xfffffc00, v1
	v_ashrrev_i32_e32 v0, 31, v8
	v_sub_u32_e32 v1, v4, v1
	v_lshrrev_b32_e32 v0, 26, v0
	v_lshrrev_b32_e32 v2, 4, v1
	v_add_u32_e32 v0, v8, v0
	v_bitop3_b32 v3, v2, v1, 32 bitop3:0x6c
	v_ashrrev_i32_e32 v1, 31, v1
	v_ashrrev_i32_e32 v0, 6, v0
	v_lshrrev_b32_e32 v1, 26, v1
	v_lshlrev_b32_e32 v2, 3, v0
	v_add_u32_e32 v1, v3, v1
	s_add_i32 s12, s79, s12
	v_and_b32_e32 v2, 0x1ffff0, v2
	v_ashrrev_i32_e32 v1, 6, v1
	s_ashr_i32 s76, s12, 31
	v_add_u32_e32 v5, v1, v2
	v_lshlrev_b32_e32 v2, 5, v0
	v_mul_i32_i24_e32 v6, 64, v1
	s_lshr_b32 s76, s76, 25
	v_and_b32_e32 v2, 32, v2
	v_sub_u32_e32 v3, v3, v6
	s_add_i32 s76, s12, s76
	v_ashrrev_i16_sdwa v3, v148, sext(v3) dst_sel:DWORD dst_unused:UNUSED_PAD src0_sel:DWORD src1_sel:BYTE_0
	v_lshl_or_b32 v5, v5, 11, v2
	s_ashr_i32 s77, s76, 7
	s_and_b32 s76, s76, 0xffffff80
	v_add_u32_sdwa v134, v5, sext(v3) dst_sel:DWORD dst_unused:UNUSED_PAD src0_sel:DWORD src1_sel:WORD_0
	v_add_u32_e32 v5, 0x2000, v4
	s_sub_i32 s89, s12, s76
	v_ashrrev_i32_e32 v4, 31, v5
	s_bfe_i32 s12, s89, 0x80000
	v_lshrrev_b32_e32 v4, 22, v4
	s_bfe_u32 s12, s12, 0x3000c
	v_add_u32_e32 v4, v5, v4
	s_add_i32 s76, s89, s12
	v_ashrrev_i32_e32 v4, 10, v4
	s_bfe_i32 s12, s76, 0x80000
	s_and_b32 s76, s76, 0xf8
	v_mul_i32_i24_e32 v6, 0x400, v4
	s_sub_i32 s76, s89, s76
	v_sub_u32_e32 v5, v5, v6
	s_lshl_b32 s77, s77, 3
	s_sext_i32_i8 s76, s76
	v_lshrrev_b32_e32 v6, 4, v5
	s_add_i32 s76, s77, s76
	v_bitop3_b32 v7, v6, v5, 32 bitop3:0x6c
	v_lshlrev_b32_e32 v5, 3, v4
	s_sext_i32_i16 s12, s12
	s_ashr_i32 s77, s76, 31
	v_and_b32_e32 v6, 0x1ffff0, v5
	v_ashrrev_i32_e32 v5, 31, v7
	s_lshr_b32 s12, s12, 3
	s_lshl_b64 s[80:81], s[76:77], 20
	v_readlane_b32 s77, v254, 48
	v_lshrrev_b32_e32 v5, 26, v5
	s_add_u32 s78, s77, s80
	v_readlane_b32 s77, v254, 49
	v_add_u32_e32 v9, v7, v5
	s_addc_u32 s79, s77, s81
	s_bfe_i64 s[82:83], s[12:13], 0x100000
	v_ashrrev_i32_e32 v5, 6, v9
	s_lshl_b64 s[82:83], s[82:83], 20
	v_add_u32_e32 v10, v5, v6
	v_lshlrev_b32_e32 v6, 5, v4
	v_and_b32_e32 v9, 0xc0, v9
	s_add_u32 s84, s2, s82
	v_readfirstlane_b32 s77, v8
	v_and_b32_e32 v6, 32, v6
	v_sub_u32_e32 v7, v7, v9
	s_addc_u32 s85, s11, s83
	s_ashr_i32 s90, s77, 6
	v_ashrrev_i16_sdwa v7, v148, sext(v7) dst_sel:DWORD dst_unused:UNUSED_PAD src0_sel:DWORD src1_sel:BYTE_0
	v_lshl_or_b32 v9, v10, 11, v6
	s_lshl_b32 s91, s90, 10
	v_add_u32_sdwa v136, v9, sext(v7) dst_sel:DWORD dst_unused:UNUSED_PAD src0_sel:DWORD src1_sel:WORD_0
	s_cmp_lg_u32 s88, s100
	v_ashrrev_i32_e32 v135, 31, v134
	v_ashrrev_i32_e32 v137, 31, v136
	s_cbranch_scc1 .LBB0_1523
	s_add_i32 s88, s91, 32
	v_lshlrev_b64 v[10:11], 1, v[134:135]
	s_add_i32 m0, s88, 0x10000
	v_lshl_add_u64 v[12:13], s[84:85], 0, v[10:11]
	global_load_lds_dwordx4 v[12:13], off
	v_lshlrev_b64 v[12:13], 1, v[136:137]
	v_lshl_add_u64 v[14:15], s[84:85], 0, v[12:13]
	s_add_i32 m0, s88, 0x12000
	s_nop 0
	global_load_lds_dwordx4 v[14:15], off
	v_lshl_add_u64 v[14:15], s[78:79], 0, v[10:11]
	s_mov_b32 m0, s88
	s_nop 0
	global_load_lds_dwordx4 v[14:15], off
	s_add_i32 m0, s88, 0x2000
	s_add_u32 s92, s84, 0x80000
	v_lshl_add_u64 v[14:15], s[78:79], 0, v[12:13]
	s_addc_u32 s93, s85, 0
	global_load_lds_dwordx4 v[14:15], off
	s_add_i32 m0, s88, 0x14000
	v_lshl_add_u64 v[14:15], s[92:93], 0, v[10:11]
	global_load_lds_dwordx4 v[14:15], off
	s_add_i32 m0, s88, 0x16000
	v_lshl_add_u64 v[14:15], s[92:93], 0, v[12:13]
	s_add_u32 s92, s78, 0x80000
	s_addc_u32 s93, s79, 0
	global_load_lds_dwordx4 v[14:15], off
	s_add_i32 m0, s88, 0x4000
	v_lshl_add_u64 v[10:11], s[92:93], 0, v[10:11]
	global_load_lds_dwordx4 v[10:11], off
	v_lshl_add_u64 v[10:11], s[92:93], 0, v[12:13]
	s_add_i32 m0, s88, 0x6000
	s_nop 0
	global_load_lds_dwordx4 v[10:11], off
